# RESID epilogue: counted vmcnt waits (4/8) instead of vmcnt(0) drains so next row-group loads stay in flight
# speedup vs baseline: 1.0068x; 1.0028x over previous
; template <int EPI>
; __device__ __forceinline__ void gemm_epilogue(const f32x4 (&acc)[2][2][4][2], const Unit& u, int wr, int wc, int fr, int fq,
;                                               const EpiArgs& ea, const float (&rs_pre)[2][4]) {
;     ...
;     EPI_LOAD_ROW(0, hc, lc, pc);
; #pragma unroll
;     for (int it = 0; it < 8; ++it) {
;       const int ai = it >> 2, m = it & 3;
;       if (it + 1 < 8) EPI_LOAD_ROW(it + 1, hn, ln_, pq);
;       const int row = row0 + ai * 128 + m * 16;
;       float sq = 0.f;
; #pragma unroll
;       for (int bj = 0; bj < 2; ++bj) {
;         const size_t idx = (size_t)row * 1024 + lcp + bj * 32;
;         const uint32_t hw[4] = {hc[bj].x, hc[bj].y, hc[bj].z, hc[bj].w};
;         const uint32_t lw[4] = {lc[bj].x, lc[bj].y, lc[bj].z, lc[bj].w};
;         const uint32_t pw[4] = {pc[bj].x, pc[bj].y, pc[bj].z, pc[bj].w};
;         uint32_t ho[4], lo_[4];
; #pragma unroll
;         for (int n = 0; n < 2; ++n) {
;           f32x4 xv;
;           xv[0] = __uint_as_float(hw[2 * n] << 16) + __uint_as_float(lw[2 * n] << 16);
;           xv[1] = __uint_as_float(hw[2 * n] & 0xffff0000u) + __uint_as_float(lw[2 * n] & 0xffff0000u);
;           xv[2] = __uint_as_float(hw[2 * n + 1] << 16) + __uint_as_float(lw[2 * n + 1] << 16);
;           xv[3] = __uint_as_float(hw[2 * n + 1] & 0xffff0000u) + __uint_as_float(lw[2 * n + 1] & 0xffff0000u);
;           const f32x4 a = acc[ai][bj][m][n];
;           f32x4 v;
;           if constexpr (EPI == EPI_PLEGATE) {
;             const float rs = rsr[ai][m], rpe = rper[ai][m];
;             const float pv[4] = {__uint_as_float(pw[2 * n] << 16), __uint_as_float(pw[2 * n] & 0xffff0000u),
;                                  __uint_as_float(pw[2 * n + 1] << 16), __uint_as_float(pw[2 * n + 1] & 0xffff0000u)};
; #pragma unroll
;             for (int i = 0; i < 4; ++i) v[i] = xv[i] + sigmoidf_(a[i] * rs) * (pv[i] * rpe);
;           } else {
;             v = xv + a * ea.alpha;
;           }
;           const uint2 hnew = pack4(v);
;           ho[2 * n] = hnew.x; ho[2 * n + 1] = hnew.y;
;           if (ea.xf32_out) {
;             *reinterpret_cast<f32x4*>(ea.xf32_out + idx + 4 * n) = v;
;           } else {
;             f32x4 r;
;             r[0] = v[0] - __uint_as_float(hnew.x << 16);
;             r[1] = v[1] - __uint_as_float(hnew.x & 0xffff0000u);
.LBB0_869:
	v_lshl_add_u32 v168, s96, 8, v174
	v_lshl_add_u32 v166, s66, 8, v176
	v_ashrrev_i32_e32 v169, 31, v168
	v_lshlrev_b64 v[130:131], 10, v[168:169]
	v_ashrrev_i32_e32 v167, 31, v166
	v_lshl_add_u64 v[130:131], v[130:131], 0, v[166:167]
	v_lshlrev_b64 v[172:173], 1, v[130:131]
	v_lshl_add_u64 v[130:131], s[68:69], 0, v[172:173]
	v_lshl_add_u64 v[132:133], s[88:89], 0, v[172:173]
	global_load_dwordx4 v[154:157], v[130:131], off
	global_load_dwordx4 v[178:181], v[132:133], off
	global_load_dwordx4 v[146:149], v[130:131], off offset:64
	global_load_dwordx4 v[150:153], v[132:133], off offset:64
	v_or_b32_e32 v130, 16, v168
	v_ashrrev_i32_e32 v131, 31, v130
	v_lshlrev_b64 v[130:131], 10, v[130:131]
	v_lshl_add_u64 v[130:131], v[130:131], 0, v[166:167]
	v_lshlrev_b64 v[170:171], 1, v[130:131]
	v_lshl_add_u64 v[130:131], s[68:69], 0, v[170:171]
	v_lshl_add_u64 v[134:135], s[88:89], 0, v[170:171]
	global_load_dwordx4 v[138:141], v[130:131], off
	global_load_dwordx4 v[142:145], v[134:135], off
	s_nop 0
	global_load_dwordx4 v[130:133], v[130:131], off offset:64
	s_nop 0
	global_load_dwordx4 v[134:137], v[134:135], off offset:64
	s_waitcnt vmcnt(4)
	v_lshlrev_b32_e32 v186, 16, v154
	v_lshlrev_b32_e32 v188, 16, v178
	v_and_b32_e32 v187, 0xffff0000, v154
	v_and_b32_e32 v189, 0xffff0000, v178
	v_lshlrev_b32_e32 v154, 16, v155
	v_lshlrev_b32_e32 v178, 16, v179
	v_and_b32_e32 v155, 0xffff0000, v155
	v_and_b32_e32 v179, 0xffff0000, v179
	v_pk_add_f32 v[186:187], v[186:187], v[188:189]
	v_pk_add_f32 v[154:155], v[154:155], v[178:179]
	v_pk_fma_f32 v[178:179], s[6:7], v[126:127], v[186:187]
	v_pk_fma_f32 v[128:129], s[60:61], v[128:129], v[154:155]
	v_cvt_pk_bf16_f32 v154, v178, v179
	s_nop 0
	v_cvt_pk_bf16_f32 v155, v128, v129
	v_lshlrev_b32_e32 v126, 16, v154
	v_and_b32_e32 v127, 0xffff0000, v154
	v_lshlrev_b32_e32 v182, 16, v155
	v_sub_f32_e32 v126, v178, v126
	v_sub_f32_e32 v127, v179, v127
	v_sub_f32_e32 v182, v128, v182
	v_and_b32_e32 v185, 0xffff0000, v155
	v_sub_f32_e32 v185, v129, v185
	v_cvt_pk_bf16_f32 v126, v126, v127
	v_cvt_pk_bf16_f32 v127, v182, v185
	v_mul_f32_e32 v182, v179, v179
	v_fmac_f32_e32 v182, v178, v178
	v_fmac_f32_e32 v182, v128, v128
	v_fmac_f32_e32 v182, v129, v129
	v_lshlrev_b32_e32 v128, 16, v156
	v_lshlrev_b32_e32 v178, 16, v180
	v_and_b32_e32 v129, 0xffff0000, v156
	v_and_b32_e32 v179, 0xffff0000, v180
	v_lshlrev_b32_e32 v156, 16, v157
	v_lshlrev_b32_e32 v180, 16, v181
	v_and_b32_e32 v157, 0xffff0000, v157
	v_and_b32_e32 v181, 0xffff0000, v181
	v_pk_add_f32 v[128:129], v[128:129], v[178:179]
	v_pk_add_f32 v[156:157], v[156:157], v[180:181]
	v_pk_fma_f32 v[122:123], s[6:7], v[122:123], v[128:129]
	v_pk_fma_f32 v[124:125], s[60:61], v[124:125], v[156:157]
	v_cvt_pk_bf16_f32 v156, v122, v123
	s_nop 0
	v_and_b32_e32 v129, 0xffff0000, v156
	v_sub_f32_e32 v129, v123, v129
	v_mul_f32_e32 v123, v123, v123
	v_fmac_f32_e32 v123, v122, v122
	v_cvt_pk_bf16_f32 v157, v124, v125
	v_lshlrev_b32_e32 v128, 16, v156
	v_lshlrev_b32_e32 v178, 16, v157
	v_fmac_f32_e32 v123, v124, v124
	v_sub_f32_e32 v128, v122, v128
	v_sub_f32_e32 v178, v124, v178
	v_and_b32_e32 v179, 0xffff0000, v157
	v_fmac_f32_e32 v123, v125, v125
	v_sub_f32_e32 v179, v125, v179
	v_cvt_pk_bf16_f32 v128, v128, v129
	v_cvt_pk_bf16_f32 v129, v178, v179
	v_add_f32_e32 v178, v182, v123
	v_lshl_add_u64 v[122:123], s[46:47], 0, v[172:173]
	v_lshl_add_u64 v[124:125], s[70:71], 0, v[172:173]
	global_store_dwordx4 v[122:123], v[154:157], off
	global_store_dwordx4 v[124:125], v[126:129], off
	s_nop 1
	v_lshlrev_b32_e32 v126, 16, v146
	v_lshlrev_b32_e32 v128, 16, v150
	v_and_b32_e32 v127, 0xffff0000, v146
	v_and_b32_e32 v129, 0xffff0000, v150
	v_lshlrev_b32_e32 v146, 16, v147
	v_lshlrev_b32_e32 v150, 16, v151
	v_and_b32_e32 v147, 0xffff0000, v147
	v_and_b32_e32 v151, 0xffff0000, v151
	v_pk_add_f32 v[126:127], v[126:127], v[128:129]
	v_pk_add_f32 v[128:129], v[146:147], v[150:151]
	s_nop 0
	v_pk_fma_f32 v[120:121], s[60:61], v[120:121], v[128:129]
	v_pk_fma_f32 v[128:129], s[6:7], v[118:119], v[126:127]
	v_cvt_pk_bf16_f32 v119, v120, v121
	s_nop 0
	v_cvt_pk_bf16_f32 v118, v128, v129
	v_lshlrev_b32_e32 v146, 16, v119
	v_and_b32_e32 v127, 0xffff0000, v118
	v_sub_f32_e32 v127, v129, v127
	v_mul_f32_e32 v129, v129, v129
	v_fmac_f32_e32 v129, v128, v128
	v_lshlrev_b32_e32 v126, 16, v118
	v_and_b32_e32 v147, 0xffff0000, v119
	v_fmac_f32_e32 v129, v120, v120
	v_sub_f32_e32 v126, v128, v126
	v_sub_f32_e32 v146, v120, v146
	v_sub_f32_e32 v147, v121, v147
	v_fmac_f32_e32 v129, v121, v121
	v_cvt_pk_bf16_f32 v126, v126, v127
	v_cvt_pk_bf16_f32 v127, v146, v147
	v_add_f32_e32 v150, v178, v129
	v_lshlrev_b32_e32 v120, 16, v148
	v_lshlrev_b32_e32 v128, 16, v152
	v_and_b32_e32 v121, 0xffff0000, v148
	v_and_b32_e32 v129, 0xffff0000, v152
	v_lshlrev_b32_e32 v146, 16, v149
	v_lshlrev_b32_e32 v148, 16, v153
	v_and_b32_e32 v147, 0xffff0000, v149
	v_and_b32_e32 v149, 0xffff0000, v153
	v_pk_add_f32 v[120:121], v[120:121], v[128:129]
	v_pk_add_f32 v[128:129], v[146:147], v[148:149]
	v_pk_fma_f32 v[114:115], s[6:7], v[114:115], v[120:121]
	v_pk_fma_f32 v[116:117], s[60:61], v[116:117], v[128:129]
	v_cvt_pk_bf16_f32 v120, v114, v115
	s_nop 0
	v_and_b32_e32 v129, 0xffff0000, v120
	v_sub_f32_e32 v129, v115, v129
	v_mul_f32_e32 v115, v115, v115
	v_fmac_f32_e32 v115, v114, v114
	v_fmac_f32_e32 v115, v116, v116
	v_lshlrev_b32_e32 v128, 16, v120
	v_fmac_f32_e32 v115, v117, v117
	v_sub_f32_e32 v128, v114, v128
	v_add_f32_e32 v114, v150, v115
	v_mov_b32_e32 v115, v114
	s_nop 1
	v_permlane16_swap_b32_e32 v114, v115
	v_cvt_pk_bf16_f32 v121, v116, v117
	v_add_f32_e32 v114, v114, v115
	v_lshlrev_b32_e32 v146, 16, v121
	v_and_b32_e32 v147, 0xffff0000, v121
	v_sub_f32_e32 v146, v116, v146
	v_sub_f32_e32 v147, v117, v147
	v_mov_b32_e32 v115, v114
	v_cvt_pk_bf16_f32 v128, v128, v129
	v_cvt_pk_bf16_f32 v129, v146, v147
	s_nop 1
	v_permlane32_swap_b32_e32 v114, v115
	v_lshl_add_u64 v[146:147], v[168:169], 2, s[62:63]
	global_store_dwordx4 v[122:123], v[118:121], off offset:64
	global_store_dwordx4 v[124:125], v[126:129], off offset:64
	s_and_saveexec_b64 s[36:37], s[0:1]
	s_cbranch_execz .LBB0_871
	v_add_f32_e32 v114, v114, v115
	global_atomic_add_f32 v[146:147], v114, off
; template <int EPI>
; __device__ __forceinline__ void gemm_epilogue(const f32x4 (&acc)[2][2][4][2], const Unit& u, int wr, int wc, int fr, int fq,
;                                               const EpiArgs& ea, const float (&rs_pre)[2][4]) {
;     ...
;       const int row = row0 + ai * 128 + m * 16;
;       float sq = 0.f;
; #pragma unroll
;       for (int bj = 0; bj < 2; ++bj) {
;         const size_t idx = (size_t)row * 1024 + lcp + bj * 32;
;         const uint32_t hw[4] = {hc[bj].x, hc[bj].y, hc[bj].z, hc[bj].w};
;         const uint32_t lw[4] = {lc[bj].x, lc[bj].y, lc[bj].z, lc[bj].w};
;         const uint32_t pw[4] = {pc[bj].x, pc[bj].y, pc[bj].z, pc[bj].w};
;         uint32_t ho[4], lo_[4];
; #pragma unroll
;         for (int n = 0; n < 2; ++n) {
;           f32x4 xv;
;           xv[0] = __uint_as_float(hw[2 * n] << 16) + __uint_as_float(lw[2 * n] << 16);
;           xv[1] = __uint_as_float(hw[2 * n] & 0xffff0000u) + __uint_as_float(lw[2 * n] & 0xffff0000u);
;           xv[2] = __uint_as_float(hw[2 * n + 1] << 16) + __uint_as_float(lw[2 * n + 1] << 16);
;           xv[3] = __uint_as_float(hw[2 * n + 1] & 0xffff0000u) + __uint_as_float(lw[2 * n + 1] & 0xffff0000u);
;           const f32x4 a = acc[ai][bj][m][n];
;           f32x4 v;
;           if constexpr (EPI == EPI_PLEGATE) {
;             const float rs = rsr[ai][m], rpe = rper[ai][m];
;             const float pv[4] = {__uint_as_float(pw[2 * n] << 16), __uint_as_float(pw[2 * n] & 0xffff0000u),
;                                  __uint_as_float(pw[2 * n + 1] << 16), __uint_as_float(pw[2 * n + 1] & 0xffff0000u)};
; #pragma unroll
;             for (int i = 0; i < 4; ++i) v[i] = xv[i] + sigmoidf_(a[i] * rs) * (pv[i] * rpe);
;           } else {
;             v = xv + a * ea.alpha;
;           }
;           const uint2 hnew = pack4(v);
;           ho[2 * n] = hnew.x; ho[2 * n + 1] = hnew.y;
;           if (ea.xf32_out) {
;             *reinterpret_cast<f32x4*>(ea.xf32_out + idx + 4 * n) = v;
;           } else {
;             f32x4 r;
;             r[0] = v[0] - __uint_as_float(hnew.x << 16);
;             r[1] = v[1] - __uint_as_float(hnew.x & 0xffff0000u);
;             r[2] = v[2] - __uint_as_float(hnew.y << 16);
;             r[3] = v[3] - __uint_as_float(hnew.y & 0xffff0000u);
;             const uint2 lnew = pack4(r);
;             lo_[2 * n] = lnew.x; lo_[2 * n + 1] = lnew.y;
;           }
.LBB0_871:
	s_waitcnt vmcnt(4)
	s_or_b64 exec, exec, s[36:37]
	v_or_b32_e32 v114, 32, v168
	v_ashrrev_i32_e32 v115, 31, v114
	v_lshlrev_b64 v[114:115], 10, v[114:115]
	v_lshl_add_u64 v[114:115], v[114:115], 0, v[166:167]
	v_lshlrev_b64 v[148:149], 1, v[114:115]
	v_lshl_add_u64 v[114:115], s[68:69], 0, v[148:149]
	v_lshl_add_u64 v[118:119], s[88:89], 0, v[148:149]
	global_load_dwordx4 v[122:125], v[114:115], off
	s_nop 0
	global_load_dwordx4 v[114:117], v[114:115], off offset:64
	s_nop 0
	global_load_dwordx4 v[126:129], v[118:119], off
	s_nop 0
	global_load_dwordx4 v[118:121], v[118:119], off offset:64
	v_lshlrev_b32_e32 v150, 16, v138
	v_lshlrev_b32_e32 v152, 16, v142
	v_and_b32_e32 v151, 0xffff0000, v138
	v_and_b32_e32 v153, 0xffff0000, v142
	v_lshlrev_b32_e32 v138, 16, v139
	v_lshlrev_b32_e32 v142, 16, v143
	v_and_b32_e32 v139, 0xffff0000, v139
	v_and_b32_e32 v143, 0xffff0000, v143
	v_pk_add_f32 v[150:151], v[150:151], v[152:153]
	v_pk_add_f32 v[138:139], v[138:139], v[142:143]
	v_pk_fma_f32 v[142:143], s[6:7], v[108:109], v[150:151]
	v_pk_fma_f32 v[110:111], s[60:61], v[110:111], v[138:139]
	v_cvt_pk_bf16_f32 v108, v142, v143
	s_nop 0
	v_cvt_pk_bf16_f32 v109, v110, v111
	v_lshlrev_b32_e32 v138, 16, v108
	v_and_b32_e32 v139, 0xffff0000, v108
	v_lshlrev_b32_e32 v150, 16, v109
	v_sub_f32_e32 v138, v142, v138
	v_sub_f32_e32 v139, v143, v139
	v_sub_f32_e32 v150, v110, v150
	v_and_b32_e32 v151, 0xffff0000, v109
	v_sub_f32_e32 v151, v111, v151
	v_cvt_pk_bf16_f32 v138, v138, v139
	v_cvt_pk_bf16_f32 v139, v150, v151
	v_mul_f32_e32 v150, v143, v143
	v_fmac_f32_e32 v150, v142, v142
	v_fmac_f32_e32 v150, v110, v110
	v_fmac_f32_e32 v150, v111, v111
	v_lshlrev_b32_e32 v110, 16, v140
	v_lshlrev_b32_e32 v142, 16, v144
	v_and_b32_e32 v111, 0xffff0000, v140
	v_and_b32_e32 v143, 0xffff0000, v144
	v_lshlrev_b32_e32 v140, 16, v141
	v_lshlrev_b32_e32 v144, 16, v145
	v_and_b32_e32 v141, 0xffff0000, v141
	v_and_b32_e32 v145, 0xffff0000, v145
	v_pk_add_f32 v[110:111], v[110:111], v[142:143]
	v_pk_add_f32 v[140:141], v[140:141], v[144:145]
	v_pk_fma_f32 v[104:105], s[6:7], v[104:105], v[110:111]
	v_pk_fma_f32 v[106:107], s[60:61], v[106:107], v[140:141]
	v_cvt_pk_bf16_f32 v110, v104, v105
	s_nop 0
	v_and_b32_e32 v141, 0xffff0000, v110
	v_sub_f32_e32 v141, v105, v141
	v_mul_f32_e32 v105, v105, v105
	v_cvt_pk_bf16_f32 v111, v106, v107
	v_lshlrev_b32_e32 v140, 16, v110
	v_lshlrev_b32_e32 v142, 16, v111
	v_and_b32_e32 v143, 0xffff0000, v111
	v_fmac_f32_e32 v105, v104, v104
	v_sub_f32_e32 v140, v104, v140
	v_sub_f32_e32 v142, v106, v142
	v_sub_f32_e32 v143, v107, v143
	v_fmac_f32_e32 v105, v106, v106
	v_cvt_pk_bf16_f32 v140, v140, v141
	v_cvt_pk_bf16_f32 v141, v142, v143
	v_fmac_f32_e32 v105, v107, v107
	v_lshl_add_u64 v[142:143], s[46:47], 0, v[170:171]
	v_add_f32_e32 v144, v150, v105
	global_store_dwordx4 v[142:143], v[108:111], off
	v_lshlrev_b32_e32 v104, 16, v130
	v_lshlrev_b32_e32 v106, 16, v134
	v_and_b32_e32 v105, 0xffff0000, v130
	v_and_b32_e32 v107, 0xffff0000, v134
	v_lshlrev_b32_e32 v110, 16, v131
	v_lshlrev_b32_e32 v130, 16, v135
	v_and_b32_e32 v111, 0xffff0000, v131
	v_and_b32_e32 v131, 0xffff0000, v135
	v_pk_add_f32 v[104:105], v[104:105], v[106:107]
	v_pk_add_f32 v[106:107], v[110:111], v[130:131]
	v_lshlrev_b32_e32 v130, 16, v137
	v_pk_fma_f32 v[102:103], s[60:61], v[102:103], v[106:107]
	v_pk_fma_f32 v[106:107], s[6:7], v[100:101], v[104:105]
	v_cvt_pk_bf16_f32 v101, v102, v103
	v_and_b32_e32 v131, 0xffff0000, v137
	v_cvt_pk_bf16_f32 v100, v106, v107
	v_lshlrev_b32_e32 v110, 16, v101
	v_and_b32_e32 v105, 0xffff0000, v100
	v_sub_f32_e32 v105, v107, v105
	v_mul_f32_e32 v107, v107, v107
	v_fmac_f32_e32 v107, v106, v106
	v_lshlrev_b32_e32 v104, 16, v100
	v_and_b32_e32 v111, 0xffff0000, v101
	v_fmac_f32_e32 v107, v102, v102
	v_sub_f32_e32 v104, v106, v104
	v_sub_f32_e32 v110, v102, v110
	v_sub_f32_e32 v111, v103, v111
	v_fmac_f32_e32 v107, v103, v103
	v_cvt_pk_bf16_f32 v104, v104, v105
	v_cvt_pk_bf16_f32 v105, v110, v111
	v_add_f32_e32 v134, v144, v107
	v_lshlrev_b32_e32 v102, 16, v132
	v_lshlrev_b32_e32 v106, 16, v136
	v_and_b32_e32 v103, 0xffff0000, v132
	v_and_b32_e32 v107, 0xffff0000, v136
	v_lshlrev_b32_e32 v110, 16, v133
	v_and_b32_e32 v111, 0xffff0000, v133
	v_pk_add_f32 v[102:103], v[102:103], v[106:107]
	v_pk_add_f32 v[106:107], v[110:111], v[130:131]
	v_pk_fma_f32 v[96:97], s[6:7], v[96:97], v[102:103]
	v_pk_fma_f32 v[98:99], s[60:61], v[98:99], v[106:107]
	v_cvt_pk_bf16_f32 v102, v96, v97
	v_lshl_add_u64 v[108:109], s[70:71], 0, v[170:171]
	v_and_b32_e32 v107, 0xffff0000, v102
	v_sub_f32_e32 v107, v97, v107
	v_mul_f32_e32 v97, v97, v97
	v_fmac_f32_e32 v97, v96, v96
	v_fmac_f32_e32 v97, v98, v98
	v_lshlrev_b32_e32 v106, 16, v102
	v_fmac_f32_e32 v97, v99, v99
	v_sub_f32_e32 v106, v96, v106
	v_add_f32_e32 v96, v134, v97
	v_mov_b32_e32 v97, v96
	s_nop 1
	v_permlane16_swap_b32_e32 v96, v97
	v_add_f32_e32 v96, v96, v97
	v_mov_b32_e32 v97, v96
	v_cvt_pk_bf16_f32 v103, v98, v99
	s_nop 1
	v_permlane32_swap_b32_e32 v96, v97
	v_lshlrev_b32_e32 v110, 16, v103
	v_and_b32_e32 v111, 0xffff0000, v103
	global_store_dwordx4 v[108:109], v[138:141], off
	v_sub_f32_e32 v110, v98, v110
	v_sub_f32_e32 v111, v99, v111
	v_cvt_pk_bf16_f32 v106, v106, v107
	v_cvt_pk_bf16_f32 v107, v110, v111
	global_store_dwordx4 v[142:143], v[100:103], off offset:64
	global_store_dwordx4 v[108:109], v[104:107], off offset:64
	s_and_saveexec_b64 s[36:37], s[0:1]
	s_cbranch_execz .LBB0_873
	v_add_f32_e32 v96, v96, v97
	global_atomic_add_f32 v[146:147], v96, off offset:64
; template <int EPI>
; __device__ __forceinline__ void gemm_epilogue(const f32x4 (&acc)[2][2][4][2], const Unit& u, int wr, int wc, int fr, int fq,
;                                               const EpiArgs& ea, const float (&rs_pre)[2][4]) {
;     ...
;       const int row = row0 + ai * 128 + m * 16;
;       float sq = 0.f;
; #pragma unroll
;       for (int bj = 0; bj < 2; ++bj) {
;         const size_t idx = (size_t)row * 1024 + lcp + bj * 32;
;         const uint32_t hw[4] = {hc[bj].x, hc[bj].y, hc[bj].z, hc[bj].w};
;         const uint32_t lw[4] = {lc[bj].x, lc[bj].y, lc[bj].z, lc[bj].w};
;         const uint32_t pw[4] = {pc[bj].x, pc[bj].y, pc[bj].z, pc[bj].w};
;         uint32_t ho[4], lo_[4];
; #pragma unroll
;         for (int n = 0; n < 2; ++n) {
;           f32x4 xv;
;           xv[0] = __uint_as_float(hw[2 * n] << 16) + __uint_as_float(lw[2 * n] << 16);
;           xv[1] = __uint_as_float(hw[2 * n] & 0xffff0000u) + __uint_as_float(lw[2 * n] & 0xffff0000u);
;           xv[2] = __uint_as_float(hw[2 * n + 1] << 16) + __uint_as_float(lw[2 * n + 1] << 16);
;           xv[3] = __uint_as_float(hw[2 * n + 1] & 0xffff0000u) + __uint_as_float(lw[2 * n + 1] & 0xffff0000u);
;           const f32x4 a = acc[ai][bj][m][n];
;           f32x4 v;
;           if constexpr (EPI == EPI_PLEGATE) {
;             const float rs = rsr[ai][m], rpe = rper[ai][m];
;             const float pv[4] = {__uint_as_float(pw[2 * n] << 16), __uint_as_float(pw[2 * n] & 0xffff0000u),
;                                  __uint_as_float(pw[2 * n + 1] << 16), __uint_as_float(pw[2 * n + 1] & 0xffff0000u)};
; #pragma unroll
;             for (int i = 0; i < 4; ++i) v[i] = xv[i] + sigmoidf_(a[i] * rs) * (pv[i] * rpe);
;           } else {
;             v = xv + a * ea.alpha;
;           }
;           const uint2 hnew = pack4(v);
;           ho[2 * n] = hnew.x; ho[2 * n + 1] = hnew.y;
;           if (ea.xf32_out) {
;             *reinterpret_cast<f32x4*>(ea.xf32_out + idx + 4 * n) = v;
;           } else {
;             f32x4 r;
;             r[0] = v[0] - __uint_as_float(hnew.x << 16);
;             r[1] = v[1] - __uint_as_float(hnew.x & 0xffff0000u);
;             r[2] = v[2] - __uint_as_float(hnew.y << 16);
;             r[3] = v[3] - __uint_as_float(hnew.y & 0xffff0000u);
;             const uint2 lnew = pack4(r);
;             lo_[2 * n] = lnew.x; lo_[2 * n + 1] = lnew.y;
;           }
.LBB0_873:
	s_or_b64 exec, exec, s[36:37]
	v_or_b32_e32 v96, 48, v168
	v_ashrrev_i32_e32 v97, 31, v96
	v_lshlrev_b64 v[96:97], 10, v[96:97]
	v_lshl_add_u64 v[96:97], v[96:97], 0, v[166:167]
	v_lshlrev_b64 v[130:131], 1, v[96:97]
	v_lshl_add_u64 v[96:97], s[68:69], 0, v[130:131]
	v_lshl_add_u64 v[100:101], s[88:89], 0, v[130:131]
	global_load_dwordx4 v[104:107], v[96:97], off
	s_nop 0
	global_load_dwordx4 v[96:99], v[96:97], off offset:64
	s_nop 0
	global_load_dwordx4 v[108:111], v[100:101], off
	s_nop 0
	global_load_dwordx4 v[100:103], v[100:101], off offset:64
	s_waitcnt vmcnt(8)
	v_lshlrev_b32_e32 v132, 16, v122
	v_lshlrev_b32_e32 v134, 16, v126
	v_and_b32_e32 v133, 0xffff0000, v122
	v_and_b32_e32 v135, 0xffff0000, v126
	v_lshlrev_b32_e32 v122, 16, v123
	v_lshlrev_b32_e32 v126, 16, v127
	v_and_b32_e32 v123, 0xffff0000, v123
	v_and_b32_e32 v127, 0xffff0000, v127
	v_pk_add_f32 v[132:133], v[132:133], v[134:135]
	v_pk_add_f32 v[122:123], v[122:123], v[126:127]
	v_pk_fma_f32 v[126:127], s[6:7], v[92:93], v[132:133]
	v_pk_fma_f32 v[94:95], s[60:61], v[94:95], v[122:123]
	v_cvt_pk_bf16_f32 v92, v126, v127
	s_nop 0
	v_cvt_pk_bf16_f32 v93, v94, v95
	v_lshlrev_b32_e32 v122, 16, v92
	v_and_b32_e32 v123, 0xffff0000, v92
	v_lshlrev_b32_e32 v132, 16, v93
	v_sub_f32_e32 v122, v126, v122
	v_sub_f32_e32 v123, v127, v123
	v_sub_f32_e32 v132, v94, v132
	v_and_b32_e32 v133, 0xffff0000, v93
	v_sub_f32_e32 v133, v95, v133
	v_cvt_pk_bf16_f32 v122, v122, v123
	v_cvt_pk_bf16_f32 v123, v132, v133
	v_mul_f32_e32 v132, v127, v127
	v_fmac_f32_e32 v132, v126, v126
	v_fmac_f32_e32 v132, v94, v94
	v_fmac_f32_e32 v132, v95, v95
	v_lshlrev_b32_e32 v94, 16, v124
	v_lshlrev_b32_e32 v126, 16, v128
	v_and_b32_e32 v95, 0xffff0000, v124
	v_and_b32_e32 v127, 0xffff0000, v128
	v_lshlrev_b32_e32 v124, 16, v125
	v_lshlrev_b32_e32 v128, 16, v129
	v_and_b32_e32 v125, 0xffff0000, v125
	v_and_b32_e32 v129, 0xffff0000, v129
	v_pk_add_f32 v[94:95], v[94:95], v[126:127]
	v_pk_add_f32 v[124:125], v[124:125], v[128:129]
	v_pk_fma_f32 v[88:89], s[6:7], v[88:89], v[94:95]
	v_pk_fma_f32 v[90:91], s[60:61], v[90:91], v[124:125]
	v_cvt_pk_bf16_f32 v94, v88, v89
	s_nop 0
	v_and_b32_e32 v125, 0xffff0000, v94
	v_sub_f32_e32 v125, v89, v125
	v_mul_f32_e32 v89, v89, v89
	v_cvt_pk_bf16_f32 v95, v90, v91
	v_lshlrev_b32_e32 v124, 16, v94
	v_lshlrev_b32_e32 v126, 16, v95
	v_and_b32_e32 v127, 0xffff0000, v95
	v_fmac_f32_e32 v89, v88, v88
	v_sub_f32_e32 v124, v88, v124
	v_sub_f32_e32 v126, v90, v126
	v_sub_f32_e32 v127, v91, v127
	v_fmac_f32_e32 v89, v90, v90
	v_cvt_pk_bf16_f32 v124, v124, v125
	v_cvt_pk_bf16_f32 v125, v126, v127
	v_fmac_f32_e32 v89, v91, v91
	v_lshl_add_u64 v[126:127], s[46:47], 0, v[148:149]
	v_add_f32_e32 v128, v132, v89
	global_store_dwordx4 v[126:127], v[92:95], off
	v_lshlrev_b32_e32 v88, 16, v114
	v_lshlrev_b32_e32 v90, 16, v118
	v_and_b32_e32 v89, 0xffff0000, v114
	v_and_b32_e32 v91, 0xffff0000, v118
	v_lshlrev_b32_e32 v94, 16, v115
	v_lshlrev_b32_e32 v114, 16, v119
	v_and_b32_e32 v95, 0xffff0000, v115
	v_and_b32_e32 v115, 0xffff0000, v119
	v_pk_add_f32 v[88:89], v[88:89], v[90:91]
	v_pk_add_f32 v[90:91], v[94:95], v[114:115]
	v_lshlrev_b32_e32 v114, 16, v121
	v_pk_fma_f32 v[86:87], s[60:61], v[86:87], v[90:91]
	v_pk_fma_f32 v[90:91], s[6:7], v[84:85], v[88:89]
	v_cvt_pk_bf16_f32 v85, v86, v87
	v_and_b32_e32 v115, 0xffff0000, v121
	v_cvt_pk_bf16_f32 v84, v90, v91
	v_lshlrev_b32_e32 v94, 16, v85
	v_and_b32_e32 v89, 0xffff0000, v84
	v_sub_f32_e32 v89, v91, v89
	v_mul_f32_e32 v91, v91, v91
	v_fmac_f32_e32 v91, v90, v90
	v_lshlrev_b32_e32 v88, 16, v84
	v_and_b32_e32 v95, 0xffff0000, v85
	v_fmac_f32_e32 v91, v86, v86
	v_sub_f32_e32 v88, v90, v88
	v_sub_f32_e32 v94, v86, v94
	v_sub_f32_e32 v95, v87, v95
	v_fmac_f32_e32 v91, v87, v87
	v_cvt_pk_bf16_f32 v88, v88, v89
	v_cvt_pk_bf16_f32 v89, v94, v95
	v_add_f32_e32 v118, v128, v91
	v_lshlrev_b32_e32 v86, 16, v116
	v_lshlrev_b32_e32 v90, 16, v120
	v_and_b32_e32 v87, 0xffff0000, v116
	v_and_b32_e32 v91, 0xffff0000, v120
	v_lshlrev_b32_e32 v94, 16, v117
	v_and_b32_e32 v95, 0xffff0000, v117
	v_pk_add_f32 v[86:87], v[86:87], v[90:91]
	v_pk_add_f32 v[90:91], v[94:95], v[114:115]
	v_pk_fma_f32 v[80:81], s[6:7], v[80:81], v[86:87]
	v_pk_fma_f32 v[82:83], s[60:61], v[82:83], v[90:91]
	v_cvt_pk_bf16_f32 v86, v80, v81
	v_lshl_add_u64 v[92:93], s[70:71], 0, v[148:149]
	v_and_b32_e32 v91, 0xffff0000, v86
	v_sub_f32_e32 v91, v81, v91
	v_mul_f32_e32 v81, v81, v81
	v_fmac_f32_e32 v81, v80, v80
	v_fmac_f32_e32 v81, v82, v82
	v_lshlrev_b32_e32 v90, 16, v86
	v_fmac_f32_e32 v81, v83, v83
	v_sub_f32_e32 v90, v80, v90
	v_add_f32_e32 v80, v118, v81
	v_mov_b32_e32 v81, v80
	s_nop 1
	v_permlane16_swap_b32_e32 v80, v81
	v_add_f32_e32 v80, v80, v81
	v_mov_b32_e32 v81, v80
	v_cvt_pk_bf16_f32 v87, v82, v83
	s_nop 1
	v_permlane32_swap_b32_e32 v80, v81
	v_lshlrev_b32_e32 v94, 16, v87
	v_and_b32_e32 v95, 0xffff0000, v87
	global_store_dwordx4 v[92:93], v[122:125], off
	v_sub_f32_e32 v94, v82, v94
	v_sub_f32_e32 v95, v83, v95
	v_cvt_pk_bf16_f32 v90, v90, v91
	v_cvt_pk_bf16_f32 v91, v94, v95
	global_store_dwordx4 v[126:127], v[84:87], off offset:64
	global_store_dwordx4 v[92:93], v[88:91], off offset:64
	s_and_saveexec_b64 s[36:37], s[0:1]
	s_cbranch_execz .LBB0_875
	v_add_f32_e32 v80, v80, v81
	global_atomic_add_f32 v[146:147], v80, off offset:128
; template <int EPI>
; __device__ __forceinline__ void gemm_epilogue(const f32x4 (&acc)[2][2][4][2], const Unit& u, int wr, int wc, int fr, int fq,
;                                               const EpiArgs& ea, const float (&rs_pre)[2][4]) {
;     ...
;       const int row = row0 + ai * 128 + m * 16;
;       float sq = 0.f;
; #pragma unroll
;       for (int bj = 0; bj < 2; ++bj) {
;         const size_t idx = (size_t)row * 1024 + lcp + bj * 32;
;         const uint32_t hw[4] = {hc[bj].x, hc[bj].y, hc[bj].z, hc[bj].w};
;         const uint32_t lw[4] = {lc[bj].x, lc[bj].y, lc[bj].z, lc[bj].w};
;         const uint32_t pw[4] = {pc[bj].x, pc[bj].y, pc[bj].z, pc[bj].w};
;         uint32_t ho[4], lo_[4];
; #pragma unroll
;         for (int n = 0; n < 2; ++n) {
;           f32x4 xv;
;           xv[0] = __uint_as_float(hw[2 * n] << 16) + __uint_as_float(lw[2 * n] << 16);
;           xv[1] = __uint_as_float(hw[2 * n] & 0xffff0000u) + __uint_as_float(lw[2 * n] & 0xffff0000u);
;           xv[2] = __uint_as_float(hw[2 * n + 1] << 16) + __uint_as_float(lw[2 * n + 1] << 16);
;           xv[3] = __uint_as_float(hw[2 * n + 1] & 0xffff0000u) + __uint_as_float(lw[2 * n + 1] & 0xffff0000u);
;           const f32x4 a = acc[ai][bj][m][n];
;           f32x4 v;
;           if constexpr (EPI == EPI_PLEGATE) {
;             const float rs = rsr[ai][m], rpe = rper[ai][m];
;             const float pv[4] = {__uint_as_float(pw[2 * n] << 16), __uint_as_float(pw[2 * n] & 0xffff0000u),
;                                  __uint_as_float(pw[2 * n + 1] << 16), __uint_as_float(pw[2 * n + 1] & 0xffff0000u)};
; #pragma unroll
;             for (int i = 0; i < 4; ++i) v[i] = xv[i] + sigmoidf_(a[i] * rs) * (pv[i] * rpe);
;           } else {
;             v = xv + a * ea.alpha;
;           }
;           const uint2 hnew = pack4(v);
;           ho[2 * n] = hnew.x; ho[2 * n + 1] = hnew.y;
;           if (ea.xf32_out) {
;             *reinterpret_cast<f32x4*>(ea.xf32_out + idx + 4 * n) = v;
;           } else {
;             f32x4 r;
;             r[0] = v[0] - __uint_as_float(hnew.x << 16);
;             r[1] = v[1] - __uint_as_float(hnew.x & 0xffff0000u);
;             r[2] = v[2] - __uint_as_float(hnew.y << 16);
;             r[3] = v[3] - __uint_as_float(hnew.y & 0xffff0000u);
;             const uint2 lnew = pack4(r);
;             lo_[2 * n] = lnew.x; lo_[2 * n + 1] = lnew.y;
;           }
.LBB0_875:
	s_waitcnt vmcnt(4)
	s_or_b64 exec, exec, s[36:37]
	v_add_u32_e32 v114, 0x80, v168
	v_ashrrev_i32_e32 v115, 31, v114
	v_lshlrev_b64 v[80:81], 10, v[114:115]
	v_lshl_add_u64 v[80:81], v[80:81], 0, v[166:167]
	v_lshlrev_b64 v[116:117], 1, v[80:81]
	v_lshl_add_u64 v[80:81], s[68:69], 0, v[116:117]
	v_lshl_add_u64 v[84:85], s[88:89], 0, v[116:117]
	global_load_dwordx4 v[88:91], v[80:81], off
	s_nop 0
	global_load_dwordx4 v[80:83], v[80:81], off offset:64
	s_nop 0
	global_load_dwordx4 v[92:95], v[84:85], off
	s_nop 0
	global_load_dwordx4 v[84:87], v[84:85], off offset:64
	v_lshlrev_b32_e32 v118, 16, v104
	v_lshlrev_b32_e32 v120, 16, v108
	v_and_b32_e32 v119, 0xffff0000, v104
	v_and_b32_e32 v121, 0xffff0000, v108
	v_lshlrev_b32_e32 v104, 16, v105
	v_lshlrev_b32_e32 v108, 16, v109
	v_and_b32_e32 v105, 0xffff0000, v105
	v_and_b32_e32 v109, 0xffff0000, v109
	v_pk_add_f32 v[118:119], v[118:119], v[120:121]
	v_pk_add_f32 v[104:105], v[104:105], v[108:109]
	v_pk_fma_f32 v[108:109], s[6:7], v[76:77], v[118:119]
	v_pk_fma_f32 v[78:79], s[60:61], v[78:79], v[104:105]
	v_cvt_pk_bf16_f32 v76, v108, v109
	s_nop 0
	v_cvt_pk_bf16_f32 v77, v78, v79
	v_lshlrev_b32_e32 v104, 16, v76
	v_and_b32_e32 v105, 0xffff0000, v76
	v_lshlrev_b32_e32 v115, 16, v77
	v_sub_f32_e32 v104, v108, v104
	v_sub_f32_e32 v105, v109, v105
	v_sub_f32_e32 v115, v78, v115
	v_and_b32_e32 v118, 0xffff0000, v77
	v_sub_f32_e32 v118, v79, v118
	v_cvt_pk_bf16_f32 v104, v104, v105
	v_cvt_pk_bf16_f32 v105, v115, v118
	v_mul_f32_e32 v115, v109, v109
	v_fmac_f32_e32 v115, v108, v108
	v_fmac_f32_e32 v115, v78, v78
	v_fmac_f32_e32 v115, v79, v79
	v_lshlrev_b32_e32 v78, 16, v106
	v_lshlrev_b32_e32 v108, 16, v110
	v_and_b32_e32 v79, 0xffff0000, v106
	v_and_b32_e32 v109, 0xffff0000, v110
	v_lshlrev_b32_e32 v106, 16, v107
	v_lshlrev_b32_e32 v110, 16, v111
	v_and_b32_e32 v107, 0xffff0000, v107
	v_and_b32_e32 v111, 0xffff0000, v111
	v_pk_add_f32 v[78:79], v[78:79], v[108:109]
	v_pk_add_f32 v[106:107], v[106:107], v[110:111]
	v_pk_fma_f32 v[72:73], s[6:7], v[72:73], v[78:79]
	v_pk_fma_f32 v[74:75], s[60:61], v[74:75], v[106:107]
	v_cvt_pk_bf16_f32 v78, v72, v73
	s_nop 0
	v_and_b32_e32 v107, 0xffff0000, v78
	v_sub_f32_e32 v107, v73, v107
	v_mul_f32_e32 v73, v73, v73
	v_cvt_pk_bf16_f32 v79, v74, v75
	v_lshlrev_b32_e32 v106, 16, v78
	v_lshlrev_b32_e32 v108, 16, v79
	v_and_b32_e32 v109, 0xffff0000, v79
	v_fmac_f32_e32 v73, v72, v72
	v_sub_f32_e32 v106, v72, v106
	v_sub_f32_e32 v108, v74, v108
	v_sub_f32_e32 v109, v75, v109
	v_fmac_f32_e32 v73, v74, v74
	v_cvt_pk_bf16_f32 v106, v106, v107
	v_cvt_pk_bf16_f32 v107, v108, v109
	v_fmac_f32_e32 v73, v75, v75
	v_lshl_add_u64 v[108:109], s[46:47], 0, v[130:131]
	v_add_f32_e32 v110, v115, v73
	global_store_dwordx4 v[108:109], v[76:79], off
	v_lshlrev_b32_e32 v72, 16, v96
	v_lshlrev_b32_e32 v74, 16, v100
	v_and_b32_e32 v73, 0xffff0000, v96
	v_and_b32_e32 v75, 0xffff0000, v100
	v_lshlrev_b32_e32 v78, 16, v97
	v_lshlrev_b32_e32 v96, 16, v101
	v_and_b32_e32 v79, 0xffff0000, v97
	v_and_b32_e32 v97, 0xffff0000, v101
	v_pk_add_f32 v[72:73], v[72:73], v[74:75]
	v_pk_add_f32 v[74:75], v[78:79], v[96:97]
	v_lshlrev_b32_e32 v96, 16, v103
	v_pk_fma_f32 v[70:71], s[60:61], v[70:71], v[74:75]
	v_pk_fma_f32 v[74:75], s[6:7], v[68:69], v[72:73]
	v_cvt_pk_bf16_f32 v69, v70, v71
	v_and_b32_e32 v97, 0xffff0000, v103
	v_cvt_pk_bf16_f32 v68, v74, v75
	v_lshlrev_b32_e32 v78, 16, v69
	v_and_b32_e32 v73, 0xffff0000, v68
	v_sub_f32_e32 v73, v75, v73
	v_mul_f32_e32 v75, v75, v75
	v_fmac_f32_e32 v75, v74, v74
	v_lshlrev_b32_e32 v72, 16, v68
	v_and_b32_e32 v79, 0xffff0000, v69
	v_fmac_f32_e32 v75, v70, v70
	v_sub_f32_e32 v72, v74, v72
	v_sub_f32_e32 v78, v70, v78
	v_sub_f32_e32 v79, v71, v79
	v_fmac_f32_e32 v75, v71, v71
	v_cvt_pk_bf16_f32 v72, v72, v73
	v_cvt_pk_bf16_f32 v73, v78, v79
	v_add_f32_e32 v100, v110, v75
	v_lshlrev_b32_e32 v70, 16, v98
	v_lshlrev_b32_e32 v74, 16, v102
	v_and_b32_e32 v71, 0xffff0000, v98
	v_and_b32_e32 v75, 0xffff0000, v102
	v_lshlrev_b32_e32 v78, 16, v99
	v_and_b32_e32 v79, 0xffff0000, v99
	v_pk_add_f32 v[70:71], v[70:71], v[74:75]
	v_pk_add_f32 v[74:75], v[78:79], v[96:97]
	v_pk_fma_f32 v[64:65], s[6:7], v[64:65], v[70:71]
	v_pk_fma_f32 v[66:67], s[60:61], v[66:67], v[74:75]
	v_cvt_pk_bf16_f32 v70, v64, v65
	v_lshl_add_u64 v[76:77], s[70:71], 0, v[130:131]
	v_and_b32_e32 v75, 0xffff0000, v70
	v_sub_f32_e32 v75, v65, v75
	v_mul_f32_e32 v65, v65, v65
	v_fmac_f32_e32 v65, v64, v64
	v_fmac_f32_e32 v65, v66, v66
	v_lshlrev_b32_e32 v74, 16, v70
	v_fmac_f32_e32 v65, v67, v67
	v_sub_f32_e32 v74, v64, v74
	v_add_f32_e32 v64, v100, v65
	v_mov_b32_e32 v65, v64
	s_nop 1
	v_permlane16_swap_b32_e32 v64, v65
	v_add_f32_e32 v64, v64, v65
	v_mov_b32_e32 v65, v64
	v_cvt_pk_bf16_f32 v71, v66, v67
	s_nop 1
	v_permlane32_swap_b32_e32 v64, v65
	v_lshlrev_b32_e32 v78, 16, v71
	v_and_b32_e32 v79, 0xffff0000, v71
	global_store_dwordx4 v[76:77], v[104:107], off
	v_sub_f32_e32 v78, v66, v78
	v_sub_f32_e32 v79, v67, v79
	v_cvt_pk_bf16_f32 v74, v74, v75
	v_cvt_pk_bf16_f32 v75, v78, v79
	global_store_dwordx4 v[108:109], v[68:71], off offset:64
	global_store_dwordx4 v[76:77], v[72:75], off offset:64
	s_and_saveexec_b64 s[36:37], s[0:1]
	s_cbranch_execz .LBB0_877
	v_add_f32_e32 v64, v64, v65
	global_atomic_add_f32 v[146:147], v64, off offset:192
; template <int EPI>
; __device__ __forceinline__ void gemm_epilogue(const f32x4 (&acc)[2][2][4][2], const Unit& u, int wr, int wc, int fr, int fq,
;                                               const EpiArgs& ea, const float (&rs_pre)[2][4]) {
;     ...
;       const int row = row0 + ai * 128 + m * 16;
;       float sq = 0.f;
; #pragma unroll
;       for (int bj = 0; bj < 2; ++bj) {
;         const size_t idx = (size_t)row * 1024 + lcp + bj * 32;
;         const uint32_t hw[4] = {hc[bj].x, hc[bj].y, hc[bj].z, hc[bj].w};
;         const uint32_t lw[4] = {lc[bj].x, lc[bj].y, lc[bj].z, lc[bj].w};
;         const uint32_t pw[4] = {pc[bj].x, pc[bj].y, pc[bj].z, pc[bj].w};
;         uint32_t ho[4], lo_[4];
; #pragma unroll
;         for (int n = 0; n < 2; ++n) {
;           f32x4 xv;
;           xv[0] = __uint_as_float(hw[2 * n] << 16) + __uint_as_float(lw[2 * n] << 16);
;           xv[1] = __uint_as_float(hw[2 * n] & 0xffff0000u) + __uint_as_float(lw[2 * n] & 0xffff0000u);
;           xv[2] = __uint_as_float(hw[2 * n + 1] << 16) + __uint_as_float(lw[2 * n + 1] << 16);
;           xv[3] = __uint_as_float(hw[2 * n + 1] & 0xffff0000u) + __uint_as_float(lw[2 * n + 1] & 0xffff0000u);
;           const f32x4 a = acc[ai][bj][m][n];
;           f32x4 v;
;           if constexpr (EPI == EPI_PLEGATE) {
;             const float rs = rsr[ai][m], rpe = rper[ai][m];
;             const float pv[4] = {__uint_as_float(pw[2 * n] << 16), __uint_as_float(pw[2 * n] & 0xffff0000u),
;                                  __uint_as_float(pw[2 * n + 1] << 16), __uint_as_float(pw[2 * n + 1] & 0xffff0000u)};
; #pragma unroll
;             for (int i = 0; i < 4; ++i) v[i] = xv[i] + sigmoidf_(a[i] * rs) * (pv[i] * rpe);
;           } else {
;             v = xv + a * ea.alpha;
;           }
;           const uint2 hnew = pack4(v);
;           ho[2 * n] = hnew.x; ho[2 * n + 1] = hnew.y;
;           if (ea.xf32_out) {
;             *reinterpret_cast<f32x4*>(ea.xf32_out + idx + 4 * n) = v;
;           } else {
;             f32x4 r;
;             r[0] = v[0] - __uint_as_float(hnew.x << 16);
;             r[1] = v[1] - __uint_as_float(hnew.x & 0xffff0000u);
;             r[2] = v[2] - __uint_as_float(hnew.y << 16);
;             r[3] = v[3] - __uint_as_float(hnew.y & 0xffff0000u);
;             const uint2 lnew = pack4(r);
;             lo_[2 * n] = lnew.x; lo_[2 * n + 1] = lnew.y;
;           }
.LBB0_877:
	s_or_b64 exec, exec, s[36:37]
	v_or_b32_e32 v64, 16, v114
	v_ashrrev_i32_e32 v65, 31, v64
	v_lshlrev_b64 v[64:65], 10, v[64:65]
	v_lshl_add_u64 v[64:65], v[64:65], 0, v[166:167]
	v_lshlrev_b64 v[96:97], 1, v[64:65]
	v_lshl_add_u64 v[64:65], s[68:69], 0, v[96:97]
	v_lshl_add_u64 v[68:69], s[88:89], 0, v[96:97]
	global_load_dwordx4 v[72:75], v[64:65], off
	s_nop 0
	global_load_dwordx4 v[64:67], v[64:65], off offset:64
	s_nop 0
	global_load_dwordx4 v[76:79], v[68:69], off
	s_nop 0
	global_load_dwordx4 v[68:71], v[68:69], off offset:64
	s_waitcnt vmcnt(8)
	v_lshlrev_b32_e32 v98, 16, v88
	v_lshlrev_b32_e32 v100, 16, v92
	v_and_b32_e32 v99, 0xffff0000, v88
	v_and_b32_e32 v101, 0xffff0000, v92
	v_lshlrev_b32_e32 v88, 16, v89
	v_lshlrev_b32_e32 v92, 16, v93
	v_and_b32_e32 v89, 0xffff0000, v89
	v_and_b32_e32 v93, 0xffff0000, v93
	v_pk_add_f32 v[98:99], v[98:99], v[100:101]
	v_pk_add_f32 v[88:89], v[88:89], v[92:93]
	v_pk_fma_f32 v[92:93], s[6:7], v[60:61], v[98:99]
	v_pk_fma_f32 v[62:63], s[60:61], v[62:63], v[88:89]
	v_cvt_pk_bf16_f32 v60, v92, v93
	s_nop 0
	v_cvt_pk_bf16_f32 v61, v62, v63
	v_lshlrev_b32_e32 v88, 16, v60
	v_and_b32_e32 v89, 0xffff0000, v60
	v_lshlrev_b32_e32 v98, 16, v61
	v_sub_f32_e32 v88, v92, v88
	v_sub_f32_e32 v89, v93, v89
	v_sub_f32_e32 v98, v62, v98
	v_and_b32_e32 v99, 0xffff0000, v61
	v_sub_f32_e32 v99, v63, v99
	v_cvt_pk_bf16_f32 v88, v88, v89
	v_cvt_pk_bf16_f32 v89, v98, v99
	v_mul_f32_e32 v98, v93, v93
	v_fmac_f32_e32 v98, v92, v92
	v_fmac_f32_e32 v98, v62, v62
	v_fmac_f32_e32 v98, v63, v63
	v_lshlrev_b32_e32 v62, 16, v90
	v_lshlrev_b32_e32 v92, 16, v94
	v_and_b32_e32 v63, 0xffff0000, v90
	v_and_b32_e32 v93, 0xffff0000, v94
	v_lshlrev_b32_e32 v90, 16, v91
	v_lshlrev_b32_e32 v94, 16, v95
	v_and_b32_e32 v91, 0xffff0000, v91
	v_and_b32_e32 v95, 0xffff0000, v95
	v_pk_add_f32 v[62:63], v[62:63], v[92:93]
	v_pk_add_f32 v[90:91], v[90:91], v[94:95]
	v_pk_fma_f32 v[56:57], s[6:7], v[56:57], v[62:63]
	v_pk_fma_f32 v[58:59], s[60:61], v[58:59], v[90:91]
	v_cvt_pk_bf16_f32 v62, v56, v57
	s_nop 0
	v_and_b32_e32 v91, 0xffff0000, v62
	v_sub_f32_e32 v91, v57, v91
	v_mul_f32_e32 v57, v57, v57
	v_cvt_pk_bf16_f32 v63, v58, v59
	v_lshlrev_b32_e32 v90, 16, v62
	v_lshlrev_b32_e32 v92, 16, v63
	v_and_b32_e32 v93, 0xffff0000, v63
	v_fmac_f32_e32 v57, v56, v56
	v_sub_f32_e32 v90, v56, v90
	v_sub_f32_e32 v92, v58, v92
	v_sub_f32_e32 v93, v59, v93
	v_fmac_f32_e32 v57, v58, v58
	v_cvt_pk_bf16_f32 v90, v90, v91
	v_cvt_pk_bf16_f32 v91, v92, v93
	v_fmac_f32_e32 v57, v59, v59
	v_lshl_add_u64 v[92:93], s[46:47], 0, v[116:117]
	v_add_f32_e32 v94, v98, v57
	global_store_dwordx4 v[92:93], v[60:63], off
	v_lshlrev_b32_e32 v56, 16, v80
	v_lshlrev_b32_e32 v58, 16, v84
	v_and_b32_e32 v57, 0xffff0000, v80
	v_and_b32_e32 v59, 0xffff0000, v84
	v_lshlrev_b32_e32 v62, 16, v81
	v_lshlrev_b32_e32 v80, 16, v85
	v_and_b32_e32 v63, 0xffff0000, v81
	v_and_b32_e32 v81, 0xffff0000, v85
	v_pk_add_f32 v[56:57], v[56:57], v[58:59]
	v_pk_add_f32 v[58:59], v[62:63], v[80:81]
	v_lshlrev_b32_e32 v80, 16, v87
	v_pk_fma_f32 v[54:55], s[60:61], v[54:55], v[58:59]
	v_pk_fma_f32 v[58:59], s[6:7], v[52:53], v[56:57]
	v_cvt_pk_bf16_f32 v53, v54, v55
	v_and_b32_e32 v81, 0xffff0000, v87
	v_cvt_pk_bf16_f32 v52, v58, v59
	v_lshlrev_b32_e32 v62, 16, v53
	v_and_b32_e32 v57, 0xffff0000, v52
	v_sub_f32_e32 v57, v59, v57
	v_mul_f32_e32 v59, v59, v59
	v_fmac_f32_e32 v59, v58, v58
	v_lshlrev_b32_e32 v56, 16, v52
	v_and_b32_e32 v63, 0xffff0000, v53
	v_fmac_f32_e32 v59, v54, v54
	v_sub_f32_e32 v56, v58, v56
	v_sub_f32_e32 v62, v54, v62
	v_sub_f32_e32 v63, v55, v63
	v_fmac_f32_e32 v59, v55, v55
	v_cvt_pk_bf16_f32 v56, v56, v57
	v_cvt_pk_bf16_f32 v57, v62, v63
	v_add_f32_e32 v84, v94, v59
	v_lshlrev_b32_e32 v54, 16, v82
	v_lshlrev_b32_e32 v58, 16, v86
	v_and_b32_e32 v55, 0xffff0000, v82
	v_and_b32_e32 v59, 0xffff0000, v86
	v_lshlrev_b32_e32 v62, 16, v83
	v_and_b32_e32 v63, 0xffff0000, v83
	v_pk_add_f32 v[54:55], v[54:55], v[58:59]
	v_pk_add_f32 v[58:59], v[62:63], v[80:81]
	v_pk_fma_f32 v[48:49], s[6:7], v[48:49], v[54:55]
	v_pk_fma_f32 v[50:51], s[60:61], v[50:51], v[58:59]
	v_cvt_pk_bf16_f32 v54, v48, v49
	v_lshl_add_u64 v[60:61], s[70:71], 0, v[116:117]
	v_and_b32_e32 v59, 0xffff0000, v54
	v_sub_f32_e32 v59, v49, v59
	v_mul_f32_e32 v49, v49, v49
	v_fmac_f32_e32 v49, v48, v48
	v_fmac_f32_e32 v49, v50, v50
	v_lshlrev_b32_e32 v58, 16, v54
	v_fmac_f32_e32 v49, v51, v51
	v_sub_f32_e32 v58, v48, v58
	v_add_f32_e32 v48, v84, v49
	v_mov_b32_e32 v49, v48
	s_nop 1
	v_permlane16_swap_b32_e32 v48, v49
	v_add_f32_e32 v48, v48, v49
	v_mov_b32_e32 v49, v48
	v_cvt_pk_bf16_f32 v55, v50, v51
	s_nop 1
	v_permlane32_swap_b32_e32 v48, v49
	v_lshlrev_b32_e32 v62, 16, v55
	v_and_b32_e32 v63, 0xffff0000, v55
	global_store_dwordx4 v[60:61], v[88:91], off
	v_sub_f32_e32 v62, v50, v62
	v_sub_f32_e32 v63, v51, v63
	v_cvt_pk_bf16_f32 v58, v58, v59
	v_cvt_pk_bf16_f32 v59, v62, v63
	global_store_dwordx4 v[92:93], v[52:55], off offset:64
	global_store_dwordx4 v[60:61], v[56:59], off offset:64
	s_and_saveexec_b64 s[36:37], s[0:1]
	s_cbranch_execz .LBB0_879
	v_add_f32_e32 v48, v48, v49
	global_atomic_add_f32 v[146:147], v48, off offset:512
; template <int EPI>
; __device__ __forceinline__ void gemm_epilogue(const f32x4 (&acc)[2][2][4][2], const Unit& u, int wr, int wc, int fr, int fq,
;                                               const EpiArgs& ea, const float (&rs_pre)[2][4]) {
;     ...
;       const int row = row0 + ai * 128 + m * 16;
;       float sq = 0.f;
; #pragma unroll
;       for (int bj = 0; bj < 2; ++bj) {
;         const size_t idx = (size_t)row * 1024 + lcp + bj * 32;
;         const uint32_t hw[4] = {hc[bj].x, hc[bj].y, hc[bj].z, hc[bj].w};
;         const uint32_t lw[4] = {lc[bj].x, lc[bj].y, lc[bj].z, lc[bj].w};
;         const uint32_t pw[4] = {pc[bj].x, pc[bj].y, pc[bj].z, pc[bj].w};
;         uint32_t ho[4], lo_[4];
; #pragma unroll
;         for (int n = 0; n < 2; ++n) {
;           f32x4 xv;
;           xv[0] = __uint_as_float(hw[2 * n] << 16) + __uint_as_float(lw[2 * n] << 16);
;           xv[1] = __uint_as_float(hw[2 * n] & 0xffff0000u) + __uint_as_float(lw[2 * n] & 0xffff0000u);
;           xv[2] = __uint_as_float(hw[2 * n + 1] << 16) + __uint_as_float(lw[2 * n + 1] << 16);
;           xv[3] = __uint_as_float(hw[2 * n + 1] & 0xffff0000u) + __uint_as_float(lw[2 * n + 1] & 0xffff0000u);
;           const f32x4 a = acc[ai][bj][m][n];
;           f32x4 v;
;           if constexpr (EPI == EPI_PLEGATE) {
;             const float rs = rsr[ai][m], rpe = rper[ai][m];
;             const float pv[4] = {__uint_as_float(pw[2 * n] << 16), __uint_as_float(pw[2 * n] & 0xffff0000u),
;                                  __uint_as_float(pw[2 * n + 1] << 16), __uint_as_float(pw[2 * n + 1] & 0xffff0000u)};
; #pragma unroll
;             for (int i = 0; i < 4; ++i) v[i] = xv[i] + sigmoidf_(a[i] * rs) * (pv[i] * rpe);
;           } else {
;             v = xv + a * ea.alpha;
;           }
;           const uint2 hnew = pack4(v);
;           ho[2 * n] = hnew.x; ho[2 * n + 1] = hnew.y;
;           if (ea.xf32_out) {
;             *reinterpret_cast<f32x4*>(ea.xf32_out + idx + 4 * n) = v;
;           } else {
;             f32x4 r;
;             r[0] = v[0] - __uint_as_float(hnew.x << 16);
;             r[1] = v[1] - __uint_as_float(hnew.x & 0xffff0000u);
;             r[2] = v[2] - __uint_as_float(hnew.y << 16);
;             r[3] = v[3] - __uint_as_float(hnew.y & 0xffff0000u);
;             const uint2 lnew = pack4(r);
;             lo_[2 * n] = lnew.x; lo_[2 * n + 1] = lnew.y;
;           }
.LBB0_879:
	s_waitcnt vmcnt(4)
	s_or_b64 exec, exec, s[36:37]
	v_or_b32_e32 v48, 32, v114
	v_ashrrev_i32_e32 v49, 31, v48
	v_lshlrev_b64 v[48:49], 10, v[48:49]
	v_lshl_add_u64 v[48:49], v[48:49], 0, v[166:167]
	v_lshlrev_b64 v[80:81], 1, v[48:49]
	v_lshl_add_u64 v[48:49], s[68:69], 0, v[80:81]
	v_lshl_add_u64 v[52:53], s[88:89], 0, v[80:81]
	global_load_dwordx4 v[56:59], v[48:49], off
	s_nop 0
	global_load_dwordx4 v[48:51], v[48:49], off offset:64
	s_nop 0
	global_load_dwordx4 v[60:63], v[52:53], off
	s_nop 0
	global_load_dwordx4 v[52:55], v[52:53], off offset:64
	v_lshlrev_b32_e32 v82, 16, v72
	v_lshlrev_b32_e32 v84, 16, v76
	v_and_b32_e32 v83, 0xffff0000, v72
	v_and_b32_e32 v85, 0xffff0000, v76
	v_lshlrev_b32_e32 v72, 16, v73
	v_lshlrev_b32_e32 v76, 16, v77
	v_and_b32_e32 v73, 0xffff0000, v73
	v_and_b32_e32 v77, 0xffff0000, v77
	v_pk_add_f32 v[82:83], v[82:83], v[84:85]
	v_pk_add_f32 v[72:73], v[72:73], v[76:77]
	v_pk_fma_f32 v[76:77], s[6:7], v[44:45], v[82:83]
	v_pk_fma_f32 v[46:47], s[60:61], v[46:47], v[72:73]
	v_cvt_pk_bf16_f32 v44, v76, v77
	s_nop 0
	v_cvt_pk_bf16_f32 v45, v46, v47
	v_lshlrev_b32_e32 v72, 16, v44
	v_and_b32_e32 v73, 0xffff0000, v44
	v_lshlrev_b32_e32 v82, 16, v45
	v_sub_f32_e32 v72, v76, v72
	v_sub_f32_e32 v73, v77, v73
	v_sub_f32_e32 v82, v46, v82
	v_and_b32_e32 v83, 0xffff0000, v45
	v_sub_f32_e32 v83, v47, v83
	v_cvt_pk_bf16_f32 v72, v72, v73
	v_cvt_pk_bf16_f32 v73, v82, v83
	v_mul_f32_e32 v82, v77, v77
	v_fmac_f32_e32 v82, v76, v76
	v_fmac_f32_e32 v82, v46, v46
	v_fmac_f32_e32 v82, v47, v47
	v_lshlrev_b32_e32 v46, 16, v74
	v_lshlrev_b32_e32 v76, 16, v78
	v_and_b32_e32 v47, 0xffff0000, v74
	v_and_b32_e32 v77, 0xffff0000, v78
	v_lshlrev_b32_e32 v74, 16, v75
	v_lshlrev_b32_e32 v78, 16, v79
	v_and_b32_e32 v75, 0xffff0000, v75
	v_and_b32_e32 v79, 0xffff0000, v79
	v_pk_add_f32 v[46:47], v[46:47], v[76:77]
	v_pk_add_f32 v[74:75], v[74:75], v[78:79]
	v_pk_fma_f32 v[40:41], s[6:7], v[40:41], v[46:47]
	v_pk_fma_f32 v[42:43], s[60:61], v[42:43], v[74:75]
	v_cvt_pk_bf16_f32 v46, v40, v41
	s_nop 0
	v_and_b32_e32 v75, 0xffff0000, v46
	v_sub_f32_e32 v75, v41, v75
	v_mul_f32_e32 v41, v41, v41
	v_cvt_pk_bf16_f32 v47, v42, v43
	v_lshlrev_b32_e32 v74, 16, v46
	v_lshlrev_b32_e32 v76, 16, v47
	v_and_b32_e32 v77, 0xffff0000, v47
	v_fmac_f32_e32 v41, v40, v40
	v_sub_f32_e32 v74, v40, v74
	v_sub_f32_e32 v76, v42, v76
	v_sub_f32_e32 v77, v43, v77
	v_fmac_f32_e32 v41, v42, v42
	v_cvt_pk_bf16_f32 v74, v74, v75
	v_cvt_pk_bf16_f32 v75, v76, v77
	v_fmac_f32_e32 v41, v43, v43
	v_lshl_add_u64 v[76:77], s[46:47], 0, v[96:97]
	v_add_f32_e32 v78, v82, v41
	global_store_dwordx4 v[76:77], v[44:47], off
	v_lshlrev_b32_e32 v40, 16, v64
	v_lshlrev_b32_e32 v42, 16, v68
	v_and_b32_e32 v41, 0xffff0000, v64
	v_and_b32_e32 v43, 0xffff0000, v68
	v_lshlrev_b32_e32 v46, 16, v65
	v_lshlrev_b32_e32 v64, 16, v69
	v_and_b32_e32 v47, 0xffff0000, v65
	v_and_b32_e32 v65, 0xffff0000, v69
	v_pk_add_f32 v[40:41], v[40:41], v[42:43]
	v_pk_add_f32 v[42:43], v[46:47], v[64:65]
	v_lshlrev_b32_e32 v64, 16, v71
	v_pk_fma_f32 v[38:39], s[60:61], v[38:39], v[42:43]
	v_pk_fma_f32 v[42:43], s[6:7], v[36:37], v[40:41]
	v_cvt_pk_bf16_f32 v37, v38, v39
	v_and_b32_e32 v65, 0xffff0000, v71
	v_cvt_pk_bf16_f32 v36, v42, v43
	v_lshlrev_b32_e32 v46, 16, v37
	v_and_b32_e32 v41, 0xffff0000, v36
	v_sub_f32_e32 v41, v43, v41
	v_mul_f32_e32 v43, v43, v43
	v_fmac_f32_e32 v43, v42, v42
	v_lshlrev_b32_e32 v40, 16, v36
	v_and_b32_e32 v47, 0xffff0000, v37
	v_fmac_f32_e32 v43, v38, v38
	v_sub_f32_e32 v40, v42, v40
	v_sub_f32_e32 v46, v38, v46
	v_sub_f32_e32 v47, v39, v47
	v_fmac_f32_e32 v43, v39, v39
	v_cvt_pk_bf16_f32 v40, v40, v41
	v_cvt_pk_bf16_f32 v41, v46, v47
	v_add_f32_e32 v68, v78, v43
	v_lshlrev_b32_e32 v38, 16, v66
	v_lshlrev_b32_e32 v42, 16, v70
	v_and_b32_e32 v39, 0xffff0000, v66
	v_and_b32_e32 v43, 0xffff0000, v70
	v_lshlrev_b32_e32 v46, 16, v67
	v_and_b32_e32 v47, 0xffff0000, v67
	v_pk_add_f32 v[38:39], v[38:39], v[42:43]
	v_pk_add_f32 v[42:43], v[46:47], v[64:65]
	v_pk_fma_f32 v[32:33], s[6:7], v[32:33], v[38:39]
	v_pk_fma_f32 v[34:35], s[60:61], v[34:35], v[42:43]
	v_cvt_pk_bf16_f32 v38, v32, v33
	v_lshl_add_u64 v[44:45], s[70:71], 0, v[96:97]
	v_and_b32_e32 v43, 0xffff0000, v38
	v_sub_f32_e32 v43, v33, v43
	v_mul_f32_e32 v33, v33, v33
	v_fmac_f32_e32 v33, v32, v32
	v_fmac_f32_e32 v33, v34, v34
	v_lshlrev_b32_e32 v42, 16, v38
	v_fmac_f32_e32 v33, v35, v35
	v_sub_f32_e32 v42, v32, v42
	v_add_f32_e32 v32, v68, v33
	v_mov_b32_e32 v33, v32
	s_nop 1
	v_permlane16_swap_b32_e32 v32, v33
	v_add_f32_e32 v32, v32, v33
	v_mov_b32_e32 v33, v32
	v_cvt_pk_bf16_f32 v39, v34, v35
	s_nop 1
	v_permlane32_swap_b32_e32 v32, v33
	v_lshlrev_b32_e32 v46, 16, v39
	v_and_b32_e32 v47, 0xffff0000, v39
	global_store_dwordx4 v[44:45], v[72:75], off
	v_sub_f32_e32 v46, v34, v46
	v_sub_f32_e32 v47, v35, v47
	v_cvt_pk_bf16_f32 v42, v42, v43
	v_cvt_pk_bf16_f32 v43, v46, v47
	global_store_dwordx4 v[76:77], v[36:39], off offset:64
	global_store_dwordx4 v[44:45], v[40:43], off offset:64
	s_and_saveexec_b64 s[36:37], s[0:1]
	s_cbranch_execz .LBB0_881
	v_add_f32_e32 v32, v32, v33
	global_atomic_add_f32 v[146:147], v32, off offset:576
; template <int EPI>
; __device__ __forceinline__ void gemm_epilogue(const f32x4 (&acc)[2][2][4][2], const Unit& u, int wr, int wc, int fr, int fq,
;                                               const EpiArgs& ea, const float (&rs_pre)[2][4]) {
;     ...
;       const int row = row0 + ai * 128 + m * 16;
;       float sq = 0.f;
; #pragma unroll
;       for (int bj = 0; bj < 2; ++bj) {
;         const size_t idx = (size_t)row * 1024 + lcp + bj * 32;
;         const uint32_t hw[4] = {hc[bj].x, hc[bj].y, hc[bj].z, hc[bj].w};
;         const uint32_t lw[4] = {lc[bj].x, lc[bj].y, lc[bj].z, lc[bj].w};
;         const uint32_t pw[4] = {pc[bj].x, pc[bj].y, pc[bj].z, pc[bj].w};
;         uint32_t ho[4], lo_[4];
; #pragma unroll
;         for (int n = 0; n < 2; ++n) {
;           f32x4 xv;
;           xv[0] = __uint_as_float(hw[2 * n] << 16) + __uint_as_float(lw[2 * n] << 16);
;           xv[1] = __uint_as_float(hw[2 * n] & 0xffff0000u) + __uint_as_float(lw[2 * n] & 0xffff0000u);
;           xv[2] = __uint_as_float(hw[2 * n + 1] << 16) + __uint_as_float(lw[2 * n + 1] << 16);
;           xv[3] = __uint_as_float(hw[2 * n + 1] & 0xffff0000u) + __uint_as_float(lw[2 * n + 1] & 0xffff0000u);
;           const f32x4 a = acc[ai][bj][m][n];
;           f32x4 v;
;           if constexpr (EPI == EPI_PLEGATE) {
;             const float rs = rsr[ai][m], rpe = rper[ai][m];
;             const float pv[4] = {__uint_as_float(pw[2 * n] << 16), __uint_as_float(pw[2 * n] & 0xffff0000u),
;                                  __uint_as_float(pw[2 * n + 1] << 16), __uint_as_float(pw[2 * n + 1] & 0xffff0000u)};
; #pragma unroll
;             for (int i = 0; i < 4; ++i) v[i] = xv[i] + sigmoidf_(a[i] * rs) * (pv[i] * rpe);
;           } else {
;             v = xv + a * ea.alpha;
;           }
;           const uint2 hnew = pack4(v);
;           ho[2 * n] = hnew.x; ho[2 * n + 1] = hnew.y;
;           if (ea.xf32_out) {
;             *reinterpret_cast<f32x4*>(ea.xf32_out + idx + 4 * n) = v;
;           } else {
;             f32x4 r;
;             r[0] = v[0] - __uint_as_float(hnew.x << 16);
;             r[1] = v[1] - __uint_as_float(hnew.x & 0xffff0000u);
;             r[2] = v[2] - __uint_as_float(hnew.y << 16);
;             r[3] = v[3] - __uint_as_float(hnew.y & 0xffff0000u);
;             const uint2 lnew = pack4(r);
;             lo_[2 * n] = lnew.x; lo_[2 * n + 1] = lnew.y;
;           }
.LBB0_881:
	s_or_b64 exec, exec, s[36:37]
	v_or_b32_e32 v32, 48, v114
	v_ashrrev_i32_e32 v33, 31, v32
	v_lshlrev_b64 v[32:33], 10, v[32:33]
	v_lshl_add_u64 v[32:33], v[32:33], 0, v[166:167]
	v_lshlrev_b64 v[64:65], 1, v[32:33]
	v_lshl_add_u64 v[32:33], s[68:69], 0, v[64:65]
	v_lshl_add_u64 v[36:37], s[88:89], 0, v[64:65]
	global_load_dwordx4 v[40:43], v[32:33], off
	s_nop 0
	global_load_dwordx4 v[32:35], v[32:33], off offset:64
	s_nop 0
	global_load_dwordx4 v[44:47], v[36:37], off
	s_nop 0
	global_load_dwordx4 v[36:39], v[36:37], off offset:64
	s_waitcnt vmcnt(8)
	v_lshlrev_b32_e32 v66, 16, v56
	v_lshlrev_b32_e32 v68, 16, v60
	v_and_b32_e32 v67, 0xffff0000, v56
	v_and_b32_e32 v69, 0xffff0000, v60
	v_lshlrev_b32_e32 v56, 16, v57
	v_lshlrev_b32_e32 v60, 16, v61
	v_and_b32_e32 v57, 0xffff0000, v57
	v_and_b32_e32 v61, 0xffff0000, v61
	v_pk_add_f32 v[66:67], v[66:67], v[68:69]
	v_pk_add_f32 v[56:57], v[56:57], v[60:61]
	v_pk_fma_f32 v[60:61], s[6:7], v[28:29], v[66:67]
	v_pk_fma_f32 v[30:31], s[60:61], v[30:31], v[56:57]
	v_cvt_pk_bf16_f32 v28, v60, v61
	s_nop 0
	v_cvt_pk_bf16_f32 v29, v30, v31
	v_lshlrev_b32_e32 v56, 16, v28
	v_and_b32_e32 v57, 0xffff0000, v28
	v_lshlrev_b32_e32 v66, 16, v29
	v_sub_f32_e32 v56, v60, v56
	v_sub_f32_e32 v57, v61, v57
	v_sub_f32_e32 v66, v30, v66
	v_and_b32_e32 v67, 0xffff0000, v29
	v_sub_f32_e32 v67, v31, v67
	v_cvt_pk_bf16_f32 v56, v56, v57
	v_cvt_pk_bf16_f32 v57, v66, v67
	v_mul_f32_e32 v66, v61, v61
	v_fmac_f32_e32 v66, v60, v60
	v_fmac_f32_e32 v66, v30, v30
	v_fmac_f32_e32 v66, v31, v31
	v_lshlrev_b32_e32 v30, 16, v58
	v_lshlrev_b32_e32 v60, 16, v62
	v_and_b32_e32 v31, 0xffff0000, v58
	v_and_b32_e32 v61, 0xffff0000, v62
	v_lshlrev_b32_e32 v58, 16, v59
	v_lshlrev_b32_e32 v62, 16, v63
	v_and_b32_e32 v59, 0xffff0000, v59
	v_and_b32_e32 v63, 0xffff0000, v63
	v_pk_add_f32 v[30:31], v[30:31], v[60:61]
	v_pk_add_f32 v[58:59], v[58:59], v[62:63]
	v_pk_fma_f32 v[24:25], s[6:7], v[24:25], v[30:31]
	v_pk_fma_f32 v[26:27], s[60:61], v[26:27], v[58:59]
	v_cvt_pk_bf16_f32 v30, v24, v25
	s_nop 0
	v_and_b32_e32 v59, 0xffff0000, v30
	v_sub_f32_e32 v59, v25, v59
	v_mul_f32_e32 v25, v25, v25
	v_cvt_pk_bf16_f32 v31, v26, v27
	v_lshlrev_b32_e32 v58, 16, v30
	v_lshlrev_b32_e32 v60, 16, v31
	v_and_b32_e32 v61, 0xffff0000, v31
	v_fmac_f32_e32 v25, v24, v24
	v_sub_f32_e32 v58, v24, v58
	v_sub_f32_e32 v60, v26, v60
	v_sub_f32_e32 v61, v27, v61
	v_fmac_f32_e32 v25, v26, v26
	v_cvt_pk_bf16_f32 v58, v58, v59
	v_cvt_pk_bf16_f32 v59, v60, v61
	v_fmac_f32_e32 v25, v27, v27
	v_lshl_add_u64 v[60:61], s[46:47], 0, v[80:81]
	v_add_f32_e32 v62, v66, v25
	global_store_dwordx4 v[60:61], v[28:31], off
	v_lshlrev_b32_e32 v24, 16, v48
	v_lshlrev_b32_e32 v26, 16, v52
	v_and_b32_e32 v25, 0xffff0000, v48
	v_and_b32_e32 v27, 0xffff0000, v52
	v_lshlrev_b32_e32 v30, 16, v49
	v_lshlrev_b32_e32 v48, 16, v53
	v_and_b32_e32 v31, 0xffff0000, v49
	v_and_b32_e32 v49, 0xffff0000, v53
	v_pk_add_f32 v[24:25], v[24:25], v[26:27]
	v_pk_add_f32 v[26:27], v[30:31], v[48:49]
	v_lshlrev_b32_e32 v48, 16, v55
	v_pk_fma_f32 v[22:23], s[60:61], v[22:23], v[26:27]
	v_pk_fma_f32 v[26:27], s[6:7], v[20:21], v[24:25]
	v_cvt_pk_bf16_f32 v21, v22, v23
	v_and_b32_e32 v49, 0xffff0000, v55
	v_cvt_pk_bf16_f32 v20, v26, v27
	v_lshlrev_b32_e32 v30, 16, v21
	v_and_b32_e32 v25, 0xffff0000, v20
	v_sub_f32_e32 v25, v27, v25
	v_mul_f32_e32 v27, v27, v27
	v_fmac_f32_e32 v27, v26, v26
	v_lshlrev_b32_e32 v24, 16, v20
	v_and_b32_e32 v31, 0xffff0000, v21
	v_fmac_f32_e32 v27, v22, v22
	v_sub_f32_e32 v24, v26, v24
	v_sub_f32_e32 v30, v22, v30
	v_sub_f32_e32 v31, v23, v31
	v_fmac_f32_e32 v27, v23, v23
	v_cvt_pk_bf16_f32 v24, v24, v25
	v_cvt_pk_bf16_f32 v25, v30, v31
	v_add_f32_e32 v52, v62, v27
	v_lshlrev_b32_e32 v22, 16, v50
	v_lshlrev_b32_e32 v26, 16, v54
	v_and_b32_e32 v23, 0xffff0000, v50
	v_and_b32_e32 v27, 0xffff0000, v54
	v_lshlrev_b32_e32 v30, 16, v51
	v_and_b32_e32 v31, 0xffff0000, v51
	v_pk_add_f32 v[22:23], v[22:23], v[26:27]
	v_pk_add_f32 v[26:27], v[30:31], v[48:49]
	v_pk_fma_f32 v[16:17], s[6:7], v[16:17], v[22:23]
	v_pk_fma_f32 v[18:19], s[60:61], v[18:19], v[26:27]
	v_cvt_pk_bf16_f32 v22, v16, v17
	v_lshl_add_u64 v[28:29], s[70:71], 0, v[80:81]
	v_and_b32_e32 v27, 0xffff0000, v22
	v_sub_f32_e32 v27, v17, v27
	v_mul_f32_e32 v17, v17, v17
	v_fmac_f32_e32 v17, v16, v16
	v_fmac_f32_e32 v17, v18, v18
	v_lshlrev_b32_e32 v26, 16, v22
	v_fmac_f32_e32 v17, v19, v19
	v_sub_f32_e32 v26, v16, v26
	v_add_f32_e32 v16, v52, v17
	v_mov_b32_e32 v17, v16
	s_nop 1
	v_permlane16_swap_b32_e32 v16, v17
	v_add_f32_e32 v16, v16, v17
	v_mov_b32_e32 v17, v16
	v_cvt_pk_bf16_f32 v23, v18, v19
	s_nop 1
	v_permlane32_swap_b32_e32 v16, v17
	v_lshlrev_b32_e32 v30, 16, v23
	v_and_b32_e32 v31, 0xffff0000, v23
	global_store_dwordx4 v[28:29], v[56:59], off
	v_sub_f32_e32 v30, v18, v30
	v_sub_f32_e32 v31, v19, v31
	v_cvt_pk_bf16_f32 v26, v26, v27
	v_cvt_pk_bf16_f32 v27, v30, v31
	global_store_dwordx4 v[60:61], v[20:23], off offset:64
	global_store_dwordx4 v[28:29], v[24:27], off offset:64
	s_and_saveexec_b64 s[36:37], s[0:1]
	s_cbranch_execz .LBB0_883
	v_add_f32_e32 v16, v16, v17
	global_atomic_add_f32 v[146:147], v16, off offset:640
; template <int EPI>
; __device__ __forceinline__ void gemm_epilogue(const f32x4 (&acc)[2][2][4][2], const Unit& u, int wr, int wc, int fr, int fq,
;                                               const EpiArgs& ea, const float (&rs_pre)[2][4]) {
;     ...
;       const int row = row0 + ai * 128 + m * 16;
;       float sq = 0.f;
; #pragma unroll
;       for (int bj = 0; bj < 2; ++bj) {
;         const size_t idx = (size_t)row * 1024 + lcp + bj * 32;
;         const uint32_t hw[4] = {hc[bj].x, hc[bj].y, hc[bj].z, hc[bj].w};
;         const uint32_t lw[4] = {lc[bj].x, lc[bj].y, lc[bj].z, lc[bj].w};
;         const uint32_t pw[4] = {pc[bj].x, pc[bj].y, pc[bj].z, pc[bj].w};
;         uint32_t ho[4], lo_[4];
; #pragma unroll
;         for (int n = 0; n < 2; ++n) {
;           f32x4 xv;
;           xv[0] = __uint_as_float(hw[2 * n] << 16) + __uint_as_float(lw[2 * n] << 16);
;           xv[1] = __uint_as_float(hw[2 * n] & 0xffff0000u) + __uint_as_float(lw[2 * n] & 0xffff0000u);
;           xv[2] = __uint_as_float(hw[2 * n + 1] << 16) + __uint_as_float(lw[2 * n + 1] << 16);
;           xv[3] = __uint_as_float(hw[2 * n + 1] & 0xffff0000u) + __uint_as_float(lw[2 * n + 1] & 0xffff0000u);
;           const f32x4 a = acc[ai][bj][m][n];
;           f32x4 v;
;           if constexpr (EPI == EPI_PLEGATE) {
;             const float rs = rsr[ai][m], rpe = rper[ai][m];
;             const float pv[4] = {__uint_as_float(pw[2 * n] << 16), __uint_as_float(pw[2 * n] & 0xffff0000u),
;                                  __uint_as_float(pw[2 * n + 1] << 16), __uint_as_float(pw[2 * n + 1] & 0xffff0000u)};
; #pragma unroll
;             for (int i = 0; i < 4; ++i) v[i] = xv[i] + sigmoidf_(a[i] * rs) * (pv[i] * rpe);
;           } else {
;             v = xv + a * ea.alpha;
;           }
;           const uint2 hnew = pack4(v);
;           ho[2 * n] = hnew.x; ho[2 * n + 1] = hnew.y;
;           if (ea.xf32_out) {
;             *reinterpret_cast<f32x4*>(ea.xf32_out + idx + 4 * n) = v;
;           } else {
;             f32x4 r;
;             r[0] = v[0] - __uint_as_float(hnew.x << 16);
;             r[1] = v[1] - __uint_as_float(hnew.x & 0xffff0000u);
;             r[2] = v[2] - __uint_as_float(hnew.y << 16);
;             r[3] = v[3] - __uint_as_float(hnew.y & 0xffff0000u);
;             const uint2 lnew = pack4(r);
;             lo_[2 * n] = lnew.x; lo_[2 * n + 1] = lnew.y;
;           }
.LBB0_883:
	s_waitcnt vmcnt(4)
	s_or_b64 exec, exec, s[36:37]
	v_lshlrev_b32_e32 v16, 16, v40
	v_lshlrev_b32_e32 v18, 16, v44
	v_and_b32_e32 v17, 0xffff0000, v40
	v_and_b32_e32 v19, 0xffff0000, v44
	v_lshlrev_b32_e32 v20, 16, v41
	v_lshlrev_b32_e32 v22, 16, v45
	v_and_b32_e32 v21, 0xffff0000, v41
	v_and_b32_e32 v23, 0xffff0000, v45
	v_pk_add_f32 v[16:17], v[16:17], v[18:19]
	v_pk_add_f32 v[18:19], v[20:21], v[22:23]
	v_lshlrev_b32_e32 v22, 16, v47
	v_pk_fma_f32 v[14:15], s[60:61], v[14:15], v[18:19]
	v_pk_fma_f32 v[18:19], s[6:7], v[12:13], v[16:17]
	v_cvt_pk_bf16_f32 v13, v14, v15
	v_and_b32_e32 v23, 0xffff0000, v47
	v_mul_f32_e32 v24, v19, v19
	v_cvt_pk_bf16_f32 v12, v18, v19
	v_lshlrev_b32_e32 v20, 16, v13
	v_lshlrev_b32_e32 v16, 16, v12
	v_and_b32_e32 v17, 0xffff0000, v12
	v_and_b32_e32 v21, 0xffff0000, v13
	v_fmac_f32_e32 v24, v18, v18
	v_sub_f32_e32 v16, v18, v16
	v_sub_f32_e32 v17, v19, v17
	v_sub_f32_e32 v20, v14, v20
	v_sub_f32_e32 v21, v15, v21
	v_fmac_f32_e32 v24, v14, v14
	v_cvt_pk_bf16_f32 v16, v16, v17
	v_cvt_pk_bf16_f32 v17, v20, v21
	v_fmac_f32_e32 v24, v15, v15
	v_lshlrev_b32_e32 v14, 16, v42
	v_lshlrev_b32_e32 v18, 16, v46
	v_and_b32_e32 v15, 0xffff0000, v42
	v_and_b32_e32 v19, 0xffff0000, v46
	v_lshlrev_b32_e32 v20, 16, v43
	v_and_b32_e32 v21, 0xffff0000, v43
	v_pk_add_f32 v[14:15], v[14:15], v[18:19]
	v_pk_add_f32 v[18:19], v[20:21], v[22:23]
	v_pk_fma_f32 v[8:9], s[6:7], v[8:9], v[14:15]
	v_pk_fma_f32 v[10:11], s[60:61], v[10:11], v[18:19]
	v_cvt_pk_bf16_f32 v14, v8, v9
	s_nop 0
	v_and_b32_e32 v19, 0xffff0000, v14
	v_cvt_pk_bf16_f32 v15, v10, v11
	v_lshlrev_b32_e32 v18, 16, v14
	v_sub_f32_e32 v19, v9, v19
	v_lshlrev_b32_e32 v20, 16, v15
	v_and_b32_e32 v21, 0xffff0000, v15
	v_mul_f32_e32 v9, v9, v9
	v_sub_f32_e32 v18, v8, v18
	v_sub_f32_e32 v20, v10, v20
	v_sub_f32_e32 v21, v11, v21
	v_fmac_f32_e32 v9, v8, v8
	v_cvt_pk_bf16_f32 v18, v18, v19
	v_cvt_pk_bf16_f32 v19, v20, v21
	v_fmac_f32_e32 v9, v10, v10
	v_lshl_add_u64 v[20:21], s[46:47], 0, v[64:65]
	v_fmac_f32_e32 v9, v11, v11
	global_store_dwordx4 v[20:21], v[12:15], off
	v_add_f32_e32 v22, v24, v9
	v_lshlrev_b32_e32 v8, 16, v32
	v_lshl_add_u64 v[12:13], s[70:71], 0, v[64:65]
	global_store_dwordx4 v[12:13], v[16:19], off
	v_lshlrev_b32_e32 v10, 16, v36
	v_and_b32_e32 v9, 0xffff0000, v32
	v_and_b32_e32 v11, 0xffff0000, v36
	v_lshlrev_b32_e32 v14, 16, v33
	v_lshlrev_b32_e32 v16, 16, v37
	v_and_b32_e32 v15, 0xffff0000, v33
	v_and_b32_e32 v17, 0xffff0000, v37
	v_pk_add_f32 v[8:9], v[8:9], v[10:11]
	v_pk_add_f32 v[10:11], v[14:15], v[16:17]
	v_lshlrev_b32_e32 v16, 16, v39
	v_pk_fma_f32 v[6:7], s[60:61], v[6:7], v[10:11]
	v_pk_fma_f32 v[10:11], s[6:7], v[4:5], v[8:9]
	v_cvt_pk_bf16_f32 v5, v6, v7
	v_and_b32_e32 v17, 0xffff0000, v39
	v_cvt_pk_bf16_f32 v4, v10, v11
	v_lshlrev_b32_e32 v14, 16, v5
	v_and_b32_e32 v9, 0xffff0000, v4
	v_sub_f32_e32 v9, v11, v9
	v_mul_f32_e32 v11, v11, v11
	v_fmac_f32_e32 v11, v10, v10
	v_lshlrev_b32_e32 v8, 16, v4
	v_and_b32_e32 v15, 0xffff0000, v5
	v_fmac_f32_e32 v11, v6, v6
	v_sub_f32_e32 v8, v10, v8
	v_sub_f32_e32 v14, v6, v14
	v_sub_f32_e32 v15, v7, v15
	v_fmac_f32_e32 v11, v7, v7
	v_cvt_pk_bf16_f32 v8, v8, v9
	v_cvt_pk_bf16_f32 v9, v14, v15
	v_add_f32_e32 v18, v22, v11
	v_lshlrev_b32_e32 v6, 16, v34
	v_lshlrev_b32_e32 v10, 16, v38
	v_and_b32_e32 v7, 0xffff0000, v34
	v_and_b32_e32 v11, 0xffff0000, v38
	v_lshlrev_b32_e32 v14, 16, v35
	v_and_b32_e32 v15, 0xffff0000, v35
	v_pk_add_f32 v[6:7], v[6:7], v[10:11]
	v_pk_add_f32 v[10:11], v[14:15], v[16:17]
	v_pk_fma_f32 v[0:1], s[6:7], v[0:1], v[6:7]
	v_pk_fma_f32 v[2:3], s[60:61], v[2:3], v[10:11]
	v_cvt_pk_bf16_f32 v6, v0, v1
	s_nop 0
	v_and_b32_e32 v11, 0xffff0000, v6
	v_sub_f32_e32 v11, v1, v11
	v_mul_f32_e32 v1, v1, v1
	v_fmac_f32_e32 v1, v0, v0
	v_fmac_f32_e32 v1, v2, v2
	v_lshlrev_b32_e32 v10, 16, v6
	v_fmac_f32_e32 v1, v3, v3
	v_sub_f32_e32 v10, v0, v10
	v_add_f32_e32 v0, v18, v1
	v_mov_b32_e32 v1, v0
	s_nop 1
	v_permlane16_swap_b32_e32 v0, v1
	v_add_f32_e32 v0, v0, v1
	v_mov_b32_e32 v1, v0
	v_cvt_pk_bf16_f32 v7, v2, v3
	s_nop 1
	v_permlane32_swap_b32_e32 v0, v1
	v_lshlrev_b32_e32 v14, 16, v7
	v_and_b32_e32 v15, 0xffff0000, v7
	v_sub_f32_e32 v14, v2, v14
	v_sub_f32_e32 v15, v3, v15
	v_cvt_pk_bf16_f32 v10, v10, v11
	v_cvt_pk_bf16_f32 v11, v14, v15
	global_store_dwordx4 v[20:21], v[4:7], off offset:64
	global_store_dwordx4 v[12:13], v[8:11], off offset:64
	s_and_saveexec_b64 s[36:37], s[0:1]
	s_cbranch_execz .LBB0_855
	v_add_f32_e32 v0, v0, v1
	global_atomic_add_f32 v[146:147], v0, off offset:704
	s_branch .LBB0_855
